# EpiScale plain-bf16 epilogue rewritten: packed scale in place, one 32-bit offset per row group on the SGPR base, no per-store mode branches (mode 1 keeps the original code)
# baseline (speedup 1.0000x reference)
; #define LAS __attribute__((address_space(3)))
;     __device__ __forceinline__ void operator()(const f32x4 (&acc)[2][2][4][2], const Unit& u, const LAS float* rsl, int wr, int wc, int fr, int fq) const {
; #pragma unroll
;         for (int ai = 0; ai < 2; ++ai)
; #pragma unroll
;             for (int m = 0; m < 4; ++m) {
;                 const int rl = ai * HALF + wr * 64 + m * 16 + fr, row = u.pm * BM + rl;
;                 const float rs = rsl[rl] * cs;
; #pragma unroll
;                 for (int bj = 0; bj < 2; ++bj) {
;                     const int col = u.pn * BM + bj * HALF + wc * 32 + 8 * fq;
;                     const f32x4 v0 = acc[ai][bj][m][0] * rs, v1 = acc[ai][bj][m][1] * rs;
;                     if (mode == 0) {
;                         *(bf16x8*)(O + (size_t)row * ldc + col) = pack8v(v0, v1);
.LBB0_504:
	s_andn2_b64 vcc, exec, s[26:27]
	s_cbranch_vccnz .Les_orig
	s_lshl_b32 s6, s7, 10
	v_add_u32_e32 v178, s6, v176
	s_lshl_b32 s51, s38, 8
	v_lshl_or_b32 v150, s36, 8, v175
	ds_read_b32 v130, v178
	ds_read_b32 v152, v178 offset:64
	ds_read_b32 v154, v178 offset:128
	ds_read_b32 v156, v178 offset:192
	ds_read_b32 v158, v178 offset:512
	ds_read_b32 v160, v178 offset:576
	ds_read_b32 v162, v178 offset:640
	ds_read_b32 v164, v178 offset:704
	s_ashr_i32 s52, s36, 2
	s_ashr_i32 s53, s52, 31
	s_lshl_b64 s[60:61], s[52:53], 20
	s_lshl_b32 s6, s52, 21
	s_ashr_i32 s52, s36, 3
	s_ashr_i32 s53, s52, 31
	s_and_b32 s49, s6, 0x200000
	s_lshl_b64 s[58:59], s[52:53], 21
	s_waitcnt lgkmcnt(0)
	v_mul_f32_e32 v130, s17, v130
	v_mul_f32_e32 v152, s17, v152
	v_mul_f32_e32 v154, s17, v154
	v_mul_f32_e32 v156, s17, v156
	v_mul_f32_e32 v158, s17, v158
	v_mul_f32_e32 v160, s17, v160
	v_mul_f32_e32 v162, s17, v162
	v_mul_f32_e32 v164, s17, v164
	v_add_u32_e32 v136, s51, v166
	v_mul_u32_u24_e32 v136, s34, v136
	v_add_lshl_u32 v136, v136, v150, 1
	v_pk_mul_f32 v[94:95], v[94:95], v[130:131] op_sel_hi:[1,0]
	v_pk_mul_f32 v[96:97], v[96:97], v[130:131] op_sel_hi:[1,0]
	v_pk_mul_f32 v[90:91], v[90:91], v[130:131] op_sel_hi:[1,0]
	v_pk_mul_f32 v[92:93], v[92:93], v[130:131] op_sel_hi:[1,0]
	v_cvt_pk_bf16_f32 v132, v94, v95
	v_cvt_pk_bf16_f32 v133, v96, v97
	v_cvt_pk_bf16_f32 v134, v90, v91
	v_cvt_pk_bf16_f32 v135, v92, v93
	global_store_dwordx4 v136, v[132:135], s[30:31]
	v_pk_mul_f32 v[62:63], v[62:63], v[130:131] op_sel_hi:[1,0]
	v_pk_mul_f32 v[64:65], v[64:65], v[130:131] op_sel_hi:[1,0]
	v_pk_mul_f32 v[58:59], v[58:59], v[130:131] op_sel_hi:[1,0]
	v_pk_mul_f32 v[60:61], v[60:61], v[130:131] op_sel_hi:[1,0]
	v_cvt_pk_bf16_f32 v182, v62, v63
	v_cvt_pk_bf16_f32 v183, v64, v65
	v_cvt_pk_bf16_f32 v184, v58, v59
	v_cvt_pk_bf16_f32 v185, v60, v61
	global_store_dwordx4 v136, v[182:185], s[30:31] offset:256
	v_add_u32_e32 v137, s51, v168
	v_mul_u32_u24_e32 v137, s34, v137
	v_add_lshl_u32 v137, v137, v150, 1
	v_pk_mul_f32 v[86:87], v[86:87], v[152:153] op_sel_hi:[1,0]
	v_pk_mul_f32 v[88:89], v[88:89], v[152:153] op_sel_hi:[1,0]
	v_pk_mul_f32 v[82:83], v[82:83], v[152:153] op_sel_hi:[1,0]
	v_pk_mul_f32 v[84:85], v[84:85], v[152:153] op_sel_hi:[1,0]
	v_cvt_pk_bf16_f32 v132, v86, v87
	v_cvt_pk_bf16_f32 v133, v88, v89
	v_cvt_pk_bf16_f32 v134, v82, v83
	v_cvt_pk_bf16_f32 v135, v84, v85
	global_store_dwordx4 v137, v[132:135], s[30:31]
	v_pk_mul_f32 v[54:55], v[54:55], v[152:153] op_sel_hi:[1,0]
	v_pk_mul_f32 v[56:57], v[56:57], v[152:153] op_sel_hi:[1,0]
	v_pk_mul_f32 v[50:51], v[50:51], v[152:153] op_sel_hi:[1,0]
	v_pk_mul_f32 v[52:53], v[52:53], v[152:153] op_sel_hi:[1,0]
	v_cvt_pk_bf16_f32 v182, v54, v55
	v_cvt_pk_bf16_f32 v183, v56, v57
	v_cvt_pk_bf16_f32 v184, v50, v51
	v_cvt_pk_bf16_f32 v185, v52, v53
	global_store_dwordx4 v137, v[182:185], s[30:31] offset:256
	v_add_u32_e32 v136, s51, v169
	v_mul_u32_u24_e32 v136, s34, v136
	v_add_lshl_u32 v136, v136, v150, 1
	v_pk_mul_f32 v[78:79], v[78:79], v[154:155] op_sel_hi:[1,0]
	v_pk_mul_f32 v[80:81], v[80:81], v[154:155] op_sel_hi:[1,0]
	v_pk_mul_f32 v[74:75], v[74:75], v[154:155] op_sel_hi:[1,0]
	v_pk_mul_f32 v[76:77], v[76:77], v[154:155] op_sel_hi:[1,0]
	v_cvt_pk_bf16_f32 v132, v78, v79
	v_cvt_pk_bf16_f32 v133, v80, v81
	v_cvt_pk_bf16_f32 v134, v74, v75
	v_cvt_pk_bf16_f32 v135, v76, v77
	global_store_dwordx4 v136, v[132:135], s[30:31]
	v_pk_mul_f32 v[46:47], v[46:47], v[154:155] op_sel_hi:[1,0]
	v_pk_mul_f32 v[48:49], v[48:49], v[154:155] op_sel_hi:[1,0]
	v_pk_mul_f32 v[42:43], v[42:43], v[154:155] op_sel_hi:[1,0]
	v_pk_mul_f32 v[44:45], v[44:45], v[154:155] op_sel_hi:[1,0]
	v_cvt_pk_bf16_f32 v182, v46, v47
	v_cvt_pk_bf16_f32 v183, v48, v49
	v_cvt_pk_bf16_f32 v184, v42, v43
	v_cvt_pk_bf16_f32 v185, v44, v45
	global_store_dwordx4 v136, v[182:185], s[30:31] offset:256
	v_add_u32_e32 v137, s51, v170
	v_mul_u32_u24_e32 v137, s34, v137
	v_add_lshl_u32 v137, v137, v150, 1
	v_pk_mul_f32 v[70:71], v[70:71], v[156:157] op_sel_hi:[1,0]
	v_pk_mul_f32 v[72:73], v[72:73], v[156:157] op_sel_hi:[1,0]
	v_pk_mul_f32 v[66:67], v[66:67], v[156:157] op_sel_hi:[1,0]
	v_pk_mul_f32 v[68:69], v[68:69], v[156:157] op_sel_hi:[1,0]
	v_cvt_pk_bf16_f32 v132, v70, v71
	v_cvt_pk_bf16_f32 v133, v72, v73
	v_cvt_pk_bf16_f32 v134, v66, v67
	v_cvt_pk_bf16_f32 v135, v68, v69
	global_store_dwordx4 v137, v[132:135], s[30:31]
; #define LAS __attribute__((address_space(3)))
;     __device__ __forceinline__ void operator()(const f32x4 (&acc)[2][2][4][2], const Unit& u, const LAS float* rsl, int wr, int wc, int fr, int fq) const {
; #pragma unroll
;         for (int ai = 0; ai < 2; ++ai)
; #pragma unroll
;             for (int m = 0; m < 4; ++m) {
;                 const int rl = ai * HALF + wr * 64 + m * 16 + fr, row = u.pm * BM + rl;
;                 const float rs = rsl[rl] * cs;
; #pragma unroll
;                 for (int bj = 0; bj < 2; ++bj) {
;                     const int col = u.pn * BM + bj * HALF + wc * 32 + 8 * fq;
;                     const f32x4 v0 = acc[ai][bj][m][0] * rs, v1 = acc[ai][bj][m][1] * rs;
;                     if (mode == 0) {
;                         *(bf16x8*)(O + (size_t)row * ldc + col) = pack8v(v0, v1);
	v_pk_mul_f32 v[38:39], v[38:39], v[156:157] op_sel_hi:[1,0]
	v_pk_mul_f32 v[40:41], v[40:41], v[156:157] op_sel_hi:[1,0]
	v_pk_mul_f32 v[34:35], v[34:35], v[156:157] op_sel_hi:[1,0]
	v_pk_mul_f32 v[36:37], v[36:37], v[156:157] op_sel_hi:[1,0]
	v_cvt_pk_bf16_f32 v182, v38, v39
	v_cvt_pk_bf16_f32 v183, v40, v41
	v_cvt_pk_bf16_f32 v184, v34, v35
	v_cvt_pk_bf16_f32 v185, v36, v37
	global_store_dwordx4 v137, v[182:185], s[30:31] offset:256
	v_add_u32_e32 v136, s51, v171
	v_mul_u32_u24_e32 v136, s34, v136
	v_add_lshl_u32 v136, v136, v150, 1
	v_pk_mul_f32 v[30:31], v[30:31], v[158:159] op_sel_hi:[1,0]
	v_pk_mul_f32 v[32:33], v[32:33], v[158:159] op_sel_hi:[1,0]
	v_pk_mul_f32 v[26:27], v[26:27], v[158:159] op_sel_hi:[1,0]
	v_pk_mul_f32 v[28:29], v[28:29], v[158:159] op_sel_hi:[1,0]
	v_cvt_pk_bf16_f32 v132, v30, v31
	v_cvt_pk_bf16_f32 v133, v32, v33
	v_cvt_pk_bf16_f32 v134, v26, v27
	v_cvt_pk_bf16_f32 v135, v28, v29
	global_store_dwordx4 v136, v[132:135], s[30:31]
	v_pk_mul_f32 v[98:99], v[98:99], v[158:159] op_sel_hi:[1,0]
	v_pk_mul_f32 v[100:101], v[100:101], v[158:159] op_sel_hi:[1,0]
	v_pk_mul_f32 v[102:103], v[102:103], v[158:159] op_sel_hi:[1,0]
	v_pk_mul_f32 v[104:105], v[104:105], v[158:159] op_sel_hi:[1,0]
	v_cvt_pk_bf16_f32 v182, v98, v99
	v_cvt_pk_bf16_f32 v183, v100, v101
	v_cvt_pk_bf16_f32 v184, v102, v103
	v_cvt_pk_bf16_f32 v185, v104, v105
	global_store_dwordx4 v136, v[182:185], s[30:31] offset:256
	v_add_u32_e32 v137, s51, v172
	v_mul_u32_u24_e32 v137, s34, v137
	v_add_lshl_u32 v137, v137, v150, 1
	v_pk_mul_f32 v[22:23], v[22:23], v[160:161] op_sel_hi:[1,0]
	v_pk_mul_f32 v[24:25], v[24:25], v[160:161] op_sel_hi:[1,0]
	v_pk_mul_f32 v[18:19], v[18:19], v[160:161] op_sel_hi:[1,0]
	v_pk_mul_f32 v[20:21], v[20:21], v[160:161] op_sel_hi:[1,0]
	v_cvt_pk_bf16_f32 v132, v22, v23
	v_cvt_pk_bf16_f32 v133, v24, v25
	v_cvt_pk_bf16_f32 v134, v18, v19
	v_cvt_pk_bf16_f32 v135, v20, v21
	global_store_dwordx4 v137, v[132:135], s[30:31]
	v_pk_mul_f32 v[106:107], v[106:107], v[160:161] op_sel_hi:[1,0]
	v_pk_mul_f32 v[108:109], v[108:109], v[160:161] op_sel_hi:[1,0]
	v_pk_mul_f32 v[110:111], v[110:111], v[160:161] op_sel_hi:[1,0]
	v_pk_mul_f32 v[112:113], v[112:113], v[160:161] op_sel_hi:[1,0]
	v_cvt_pk_bf16_f32 v182, v106, v107
	v_cvt_pk_bf16_f32 v183, v108, v109
	v_cvt_pk_bf16_f32 v184, v110, v111
	v_cvt_pk_bf16_f32 v185, v112, v113
	global_store_dwordx4 v137, v[182:185], s[30:31] offset:256
	v_add_u32_e32 v136, s51, v173
	v_mul_u32_u24_e32 v136, s34, v136
	v_add_lshl_u32 v136, v136, v150, 1
	v_pk_mul_f32 v[14:15], v[14:15], v[162:163] op_sel_hi:[1,0]
	v_pk_mul_f32 v[16:17], v[16:17], v[162:163] op_sel_hi:[1,0]
	v_pk_mul_f32 v[10:11], v[10:11], v[162:163] op_sel_hi:[1,0]
	v_pk_mul_f32 v[12:13], v[12:13], v[162:163] op_sel_hi:[1,0]
	v_cvt_pk_bf16_f32 v132, v14, v15
	v_cvt_pk_bf16_f32 v133, v16, v17
	v_cvt_pk_bf16_f32 v134, v10, v11
	v_cvt_pk_bf16_f32 v135, v12, v13
	global_store_dwordx4 v136, v[132:135], s[30:31]
	v_pk_mul_f32 v[114:115], v[114:115], v[162:163] op_sel_hi:[1,0]
	v_pk_mul_f32 v[116:117], v[116:117], v[162:163] op_sel_hi:[1,0]
	v_pk_mul_f32 v[118:119], v[118:119], v[162:163] op_sel_hi:[1,0]
	v_pk_mul_f32 v[120:121], v[120:121], v[162:163] op_sel_hi:[1,0]
	v_cvt_pk_bf16_f32 v182, v114, v115
	v_cvt_pk_bf16_f32 v183, v116, v117
	v_cvt_pk_bf16_f32 v184, v118, v119
	v_cvt_pk_bf16_f32 v185, v120, v121
	global_store_dwordx4 v136, v[182:185], s[30:31] offset:256
	v_add_u32_e32 v137, s51, v174
	v_mul_u32_u24_e32 v137, s34, v137
	v_add_lshl_u32 v137, v137, v150, 1
	v_pk_mul_f32 v[6:7], v[6:7], v[164:165] op_sel_hi:[1,0]
	v_pk_mul_f32 v[8:9], v[8:9], v[164:165] op_sel_hi:[1,0]
	v_pk_mul_f32 v[2:3], v[2:3], v[164:165] op_sel_hi:[1,0]
	v_pk_mul_f32 v[4:5], v[4:5], v[164:165] op_sel_hi:[1,0]
	v_cvt_pk_bf16_f32 v132, v6, v7
	v_cvt_pk_bf16_f32 v133, v8, v9
	v_cvt_pk_bf16_f32 v134, v2, v3
	v_cvt_pk_bf16_f32 v135, v4, v5
	global_store_dwordx4 v137, v[132:135], s[30:31]
	v_pk_mul_f32 v[122:123], v[122:123], v[164:165] op_sel_hi:[1,0]
	v_pk_mul_f32 v[124:125], v[124:125], v[164:165] op_sel_hi:[1,0]
	v_pk_mul_f32 v[126:127], v[126:127], v[164:165] op_sel_hi:[1,0]
	v_pk_mul_f32 v[128:129], v[128:129], v[164:165] op_sel_hi:[1,0]
	v_cvt_pk_bf16_f32 v182, v122, v123
	v_cvt_pk_bf16_f32 v183, v124, v125
	v_cvt_pk_bf16_f32 v184, v126, v127
	v_cvt_pk_bf16_f32 v185, v128, v129
	global_store_dwordx4 v137, v[182:185], s[30:31] offset:256
	v_readlane_b32 s68, v255, 12
	s_branch .LBB0_566
